# v15 + P6 rotary epilogue: cos/sin loads of all 8 row blocks issued up front for rotating waves, per-block vmcnt(0) only in the rotating path
# baseline (speedup 1.0000x reference)
; #define PG8_LAS __attribute__((address_space(3)))
; template <int LAYOUT> __device__ __forceinline__ void staged_store_bf16(PG8_LAS unsigned char* stg, bf16_t* O, size_t ldc, int rowg0, int pn, int wc, int lane) {
;     const int p = lane & 7;
; #pragma unroll
;     for (int hr = 0; hr < 2; ++hr) { const int r = 8 * hr + (lane >> 3), rowg = rowg0 + r; const u32x4 w = *(const PG8_LAS u32x4*)(stg + r * STG_ROW + p * 16);
;         if (LAYOUT == 0) __builtin_nontemporal_store(w, (u32x4*)(O + (size_t)rowg * ldc + pn * BM + wc * 64 + p * 8));
;         else { const int P = 2 * pn + (wc >> 1); int drow = rowg;
;             if (LAYOUT == 2) { const int sh = 2 * (P / 24), t = rowg & 16383; drow = (rowg & ~16383) + ((t & ((1 << sh) - 1)) << (14 - sh)) + (t >> sh); }
;     __device__ __forceinline__ void operator()(const f32x4 (&acc)[2][2][4][2], const Unit& u, int wr, int wc, int fr, int fq) const {
;         const int lane = fr + 16 * fq; PG8_LAS unsigned char* stg = lds + STG_OFF + (wr * 4 + wc) * STG_WAVE;
;         const bool rot = ((wc & 1) == 0) && (((u.pn >> 2) % 3) != 2);
;         const PG8_LAS float* rtab = (const PG8_LAS float*)(lds + RSTD_OFF) + ((u.pm >> 3) & 3) * 256;
; #pragma unroll
;         for (int ai = 0; ai < 2; ++ai)
; #pragma unroll
;             for (int m = 0; m < 4; ++m) {
;                 const int rowg0 = u.pm * BM + ai * HALF + wr * 64 + m * 16, row = rowg0 + fr; const float rs = rtab[ai * HALF + wr * 64 + m * 16 + fr];
;                 f32x4 c4 = {1.f, 1.f, 1.f, 1.f}, s4 = {0.f, 0.f, 0.f, 0.f};
;                 if (rot) { const int t = row & 16383; c4 = *(const f32x4*)(cst + t * 16 + 4 * fq); s4 = *(const f32x4*)(snt + t * 16 + 4 * fq); }
; #pragma unroll
;                 for (int bj = 0; bj < 2; ++bj) {
;                     const f32x4 a = acc[ai][bj][m][0] * rs, b = acc[ai][bj][m][1] * rs;
;                     const f32x4 a2 = (bj == 0) ? a * c4 - b * s4 : a, b2 = (bj == 0) ? b * c4 + a * s4 : b;
;                     u32x2 w0, w1; w0.x = cvt_pk_bf16(a2[0], a2[1]); w0.y = cvt_pk_bf16(a2[2], a2[3]); w1.x = cvt_pk_bf16(b2[0], b2[1]); w1.y = cvt_pk_bf16(b2[2], b2[3]);
;                     *(PG8_LAS u32x2*)(stg + fr * STG_ROW + bj * 64 + fq * 8) = w0; *(PG8_LAS u32x2*)(stg + fr * STG_ROW + bj * 64 + 32 + fq * 8) = w1; }
;                 staged_store_bf16<2>(stg, O, (size_t)ldc, rowg0, u.pn, wc, lane);
.LBB0_602:
	s_lshl_b32 s62, s10, 8
	s_lshl_b32 s10, s10, 7
	s_and_b32 s10, s10, 0xc00
	v_add_u32_e32 v184, s10, v170
	ds_read_b32 v130, v184
	v_cndmask_b32_e64 v129, 0, 1, s[60:61]
	s_add_i32 s62, s62, s73
	v_mov_b32_e32 v128, 1.0
	v_mov_b32_e32 v132, 0
	v_cmp_ne_u32_e64 s[10:11], 1, v129
	s_andn2_b64 vcc, exec, s[60:61]
	v_mov_b32_e32 v134, 0
	v_mov_b32_e32 v135, 0
	v_mov_b32_e32 v136, 0
	v_mov_b32_e32 v137, 0
	v_mov_b32_e32 v138, 1.0
	v_mov_b32_e32 v139, 1.0
	v_mov_b32_e32 v140, 1.0
	v_mov_b32_e32 v141, 1.0
	s_cbranch_vccnz .LBB0_604
	s_and_b32 s26, s62, 0x3fc0
	v_or_b32_e32 v129, s26, v166
	v_lshlrev_b32_e32 v150, 6, v129
	v_lshl_add_u64 v[134:135], v[152:153], 0, v[150:151]
	v_lshl_add_u64 v[136:137], v[154:155], 0, v[150:151]
	global_load_dwordx4 v[138:141], v[136:137], off
	s_nop 0
	global_load_dwordx4 v[134:137], v[134:135], off
	v_mov_b32_e32 v187, 0
	s_or_b32 s100, s62, 16
	s_and_b32 s100, s100, 0x3fd0
	v_or_b32_e32 v186, s100, v166
	v_lshlrev_b32_e32 v186, 6, v186
	v_lshl_add_u64 v[248:249], v[154:155], 0, v[186:187]
	v_lshl_add_u64 v[250:251], v[152:153], 0, v[186:187]
	global_load_dwordx4 v[190:193], v[248:249], off
	global_load_dwordx4 v[194:197], v[250:251], off
	s_nop 1
	s_or_b32 s100, s62, 32
	s_and_b32 s100, s100, 0x3fe0
	v_or_b32_e32 v186, s100, v166
	v_lshlrev_b32_e32 v186, 6, v186
	v_lshl_add_u64 v[248:249], v[154:155], 0, v[186:187]
	v_lshl_add_u64 v[250:251], v[152:153], 0, v[186:187]
	global_load_dwordx4 v[198:201], v[248:249], off
	global_load_dwordx4 v[202:205], v[250:251], off
	s_nop 1
	s_or_b32 s100, s62, 48
	s_and_b32 s100, s100, 0x3ff0
	v_or_b32_e32 v186, s100, v166
	v_lshlrev_b32_e32 v186, 6, v186
	v_lshl_add_u64 v[248:249], v[154:155], 0, v[186:187]
	v_lshl_add_u64 v[250:251], v[152:153], 0, v[186:187]
	global_load_dwordx4 v[206:209], v[248:249], off
	global_load_dwordx4 v[212:215], v[250:251], off
	s_nop 1
	s_add_i32 s100, s62, 0x80
	s_or_b32 s100, s100, 0
	s_and_b32 s100, s100, 0x3fc0
	v_or_b32_e32 v186, s100, v166
	v_lshlrev_b32_e32 v186, 6, v186
	v_lshl_add_u64 v[248:249], v[154:155], 0, v[186:187]
	v_lshl_add_u64 v[250:251], v[152:153], 0, v[186:187]
	global_load_dwordx4 v[216:219], v[248:249], off
	global_load_dwordx4 v[220:223], v[250:251], off
	s_nop 1
	s_add_i32 s100, s62, 0x80
	s_or_b32 s100, s100, 16
	s_and_b32 s100, s100, 0x3fd0
	v_or_b32_e32 v186, s100, v166
	v_lshlrev_b32_e32 v186, 6, v186
	v_lshl_add_u64 v[248:249], v[154:155], 0, v[186:187]
	v_lshl_add_u64 v[250:251], v[152:153], 0, v[186:187]
	global_load_dwordx4 v[224:227], v[248:249], off
	global_load_dwordx4 v[228:231], v[250:251], off
	s_nop 1
	s_add_i32 s100, s62, 0x80
	s_or_b32 s100, s100, 32
	s_and_b32 s100, s100, 0x3fe0
	v_or_b32_e32 v186, s100, v166
	v_lshlrev_b32_e32 v186, 6, v186
	v_lshl_add_u64 v[248:249], v[154:155], 0, v[186:187]
	v_lshl_add_u64 v[250:251], v[152:153], 0, v[186:187]
	global_load_dwordx4 v[232:235], v[248:249], off
	global_load_dwordx4 v[236:239], v[250:251], off
	s_nop 1
	s_add_i32 s100, s62, 0x80
	s_or_b32 s100, s100, 48
	s_and_b32 s100, s100, 0x3ff0
	v_or_b32_e32 v186, s100, v166
	v_lshlrev_b32_e32 v186, 6, v186
	v_lshl_add_u64 v[248:249], v[154:155], 0, v[186:187]
	v_lshl_add_u64 v[250:251], v[152:153], 0, v[186:187]
	global_load_dwordx4 v[240:243], v[248:249], off
	global_load_dwordx4 v[244:247], v[250:251], off
	s_nop 1
	s_waitcnt vmcnt(0)
.LBB0_604:
	s_lshl_b32 s26, s58, 1
	s_or_b32 s26, s26, s76
	s_mul_hi_i32 s27, s26, 0x2aaaaaab
	s_lshr_b32 s33, s27, 31
	s_ashr_i32 s27, s27, 2
	s_waitcnt lgkmcnt(0)
	v_pk_mul_f32 v[120:121], v[120:121], v[130:131] op_sel_hi:[1,0]
	s_add_i32 s27, s27, s33
	v_pk_mul_f32 v[124:125], v[124:125], v[130:131] op_sel_hi:[1,0]
	v_pk_mul_f32 v[122:123], v[122:123], v[130:131] op_sel_hi:[1,0]
	v_pk_mul_f32 v[186:187], v[120:121], v[134:135]
	v_pk_mul_f32 v[120:121], v[120:121], v[138:139]
	s_lshl_b32 s51, s27, 1
	v_pk_mul_f32 v[126:127], v[126:127], v[130:131] op_sel_hi:[1,0]
	v_pk_mul_f32 v[188:189], v[122:123], v[136:137]
	v_pk_mul_f32 v[122:123], v[122:123], v[140:141]
	v_pk_fma_f32 v[120:121], v[124:125], v[134:135], v[120:121]
	v_pk_mul_f32 v[116:117], v[116:117], v[130:131] op_sel_hi:[1,0]
	v_pk_mul_f32 v[114:115], v[114:115], v[130:131] op_sel_hi:[1,0]
	v_pk_mul_f32 v[112:113], v[112:113], v[130:131] op_sel_hi:[1,0]
	s_sub_i32 s53, 14, s51
	v_pk_fma_f32 v[188:189], v[126:127], v[140:141], v[188:189] neg_lo:[0,0,1] neg_hi:[0,0,1]
	v_pk_fma_f32 v[186:187], v[124:125], v[138:139], v[186:187] neg_lo:[0,0,1] neg_hi:[0,0,1]
	v_pk_fma_f32 v[122:123], v[126:127], v[136:137], v[122:123]
	v_cvt_pk_bf16_f32 v124, v186, v187
	v_cvt_pk_bf16_f32 v125, v188, v189
	v_cvt_pk_bf16_f32 v120, v120, v121
	v_pk_mul_f32 v[118:119], v[118:119], v[130:131] op_sel_hi:[1,0]
	v_cvt_pk_bf16_f32 v121, v122, v123
	ds_write2_b64 v174, v[124:125], v[120:121] offset1:4
	v_cvt_pk_bf16_f32 v116, v116, v117
	v_cvt_pk_bf16_f32 v117, v118, v119
	v_cvt_pk_bf16_f32 v112, v112, v113
	v_cvt_pk_bf16_f32 v113, v114, v115
	v_or_b32_e32 v114, s62, v168
	v_bitop3_b32 v115, s62, v176, v168 bitop3:0xc8
	s_and_b32 s58, s62, 0xffffc000
	ds_write2_b64 v174, v[116:117], v[112:113] offset0:8 offset1:12
	v_lshlrev_b32_e32 v114, s53, v114
	v_lshrrev_b32_e32 v115, s51, v115
	ds_read_b128 v[116:119], v175
	v_and_b32_e32 v114, 0x3fff, v114
	v_or_b32_e32 v115, s58, v115
	s_ashr_i32 s27, s26, 31
	v_add_u32_e32 v114, v115, v114
	s_lshl_b64 s[26:27], s[26:27], 23
	v_ashrrev_i32_e32 v115, 31, v114
	v_lshl_add_u64 v[112:113], v[156:157], 0, s[26:27]
	v_lshlrev_b64 v[114:115], 8, v[114:115]
	v_lshl_add_u64 v[120:121], v[112:113], 0, v[114:115]
	ds_read_b32 v114, v184 offset:64
	s_waitcnt lgkmcnt(1)
	global_store_dwordx4 v[120:121], v[116:119], off nt
	v_or_b32_e32 v115, s62, v169
	v_bitop3_b32 v120, s62, v177, v169 bitop3:0xc8
	v_lshlrev_b32_e32 v115, s53, v115
	v_lshrrev_b32_e32 v120, s51, v120
	ds_read_b128 v[116:119], v175 offset:1152
	v_and_b32_e32 v115, 0x3fff, v115
	v_or_b32_e32 v120, s58, v120
	v_add_u32_e32 v120, v120, v115
	v_ashrrev_i32_e32 v121, 31, v120
	v_lshlrev_b64 v[120:121], 8, v[120:121]
	v_lshl_add_u64 v[120:121], v[112:113], 0, v[120:121]
	s_or_b32 s26, s62, 16
	s_and_b64 vcc, exec, s[10:11]
	v_mov_b32_e32 v133, 0
	v_mov_b32_e32 v134, 0
	v_mov_b32_e32 v135, 0
	v_mov_b32_e32 v129, 1.0
	v_mov_b32_e32 v130, 1.0
	v_mov_b32_e32 v131, 1.0
	s_waitcnt lgkmcnt(0)
	global_store_dwordx4 v[120:121], v[116:119], off nt
	s_cbranch_vccnz .LBB0_606
	v_mov_b64_e32 v[128:129], v[190:191]
	v_mov_b64_e32 v[130:131], v[192:193]
	v_mov_b64_e32 v[132:133], v[194:195]
	v_mov_b64_e32 v[134:135], v[196:197]
; #define PG8_LAS __attribute__((address_space(3)))
; __device__ __forceinline__ unsigned cvt_pk_bf16(float lo, float hi) { unsigned r; asm volatile("v_cvt_pk_bf16_f32 %0, %1, %2" : "=v"(r) : "v"(lo), "v"(hi)); return r; }
; template <int LAYOUT> __device__ __forceinline__ void staged_store_bf16(PG8_LAS unsigned char* stg, bf16_t* O, size_t ldc, int rowg0, int pn, int wc, int lane) {
;     const int p = lane & 7;
; #pragma unroll
;     for (int hr = 0; hr < 2; ++hr) { const int r = 8 * hr + (lane >> 3), rowg = rowg0 + r; const u32x4 w = *(const PG8_LAS u32x4*)(stg + r * STG_ROW + p * 16);
;         if (LAYOUT == 0) __builtin_nontemporal_store(w, (u32x4*)(O + (size_t)rowg * ldc + pn * BM + wc * 64 + p * 8));
;         else { const int P = 2 * pn + (wc >> 1); int drow = rowg;
;             if (LAYOUT == 2) { const int sh = 2 * (P / 24), t = rowg & 16383; drow = (rowg & ~16383) + ((t & ((1 << sh) - 1)) << (14 - sh)) + (t >> sh); }
;             __builtin_nontemporal_store(w, (u32x4*)(O + (size_t)P * PLANE + (size_t)drow * 128 + (wc & 1) * 64 + p * 8)); } }
;     __device__ __forceinline__ void operator()(const f32x4 (&acc)[2][2][4][2], const Unit& u, int wr, int wc, int fr, int fq) const {
;     ...
;                 const int rowg0 = u.pm * BM + ai * HALF + wr * 64 + m * 16, row = rowg0 + fr; const float rs = rtab[ai * HALF + wr * 64 + m * 16 + fr];
;                 f32x4 c4 = {1.f, 1.f, 1.f, 1.f}, s4 = {0.f, 0.f, 0.f, 0.f};
;                 if (rot) { const int t = row & 16383; c4 = *(const f32x4*)(cst + t * 16 + 4 * fq); s4 = *(const f32x4*)(snt + t * 16 + 4 * fq); }
; #pragma unroll
;                 for (int bj = 0; bj < 2; ++bj) {
;                     const f32x4 a = acc[ai][bj][m][0] * rs, b = acc[ai][bj][m][1] * rs;
;                     const f32x4 a2 = (bj == 0) ? a * c4 - b * s4 : a, b2 = (bj == 0) ? b * c4 + a * s4 : b;
;                     u32x2 w0, w1; w0.x = cvt_pk_bf16(a2[0], a2[1]); w0.y = cvt_pk_bf16(a2[2], a2[3]); w1.x = cvt_pk_bf16(b2[0], b2[1]); w1.y = cvt_pk_bf16(b2[2], b2[3]);
;                     *(PG8_LAS u32x2*)(stg + fr * STG_ROW + bj * 64 + fq * 8) = w0; *(PG8_LAS u32x2*)(stg + fr * STG_ROW + bj * 64 + 32 + fq * 8) = w1; }
;                 staged_store_bf16<2>(stg, O, (size_t)ldc, rowg0, u.pn, wc, lane);
.LBB0_606:
	v_pk_mul_f32 v[104:105], v[104:105], v[114:115] op_sel_hi:[1,0]
	v_pk_mul_f32 v[108:109], v[108:109], v[114:115] op_sel_hi:[1,0]
	v_pk_mul_f32 v[106:107], v[106:107], v[114:115] op_sel_hi:[1,0]
	v_pk_mul_f32 v[116:117], v[104:105], v[132:133]
	v_pk_mul_f32 v[104:105], v[104:105], v[128:129]
	v_pk_mul_f32 v[110:111], v[110:111], v[114:115] op_sel_hi:[1,0]
	v_pk_mul_f32 v[118:119], v[106:107], v[134:135]
	v_pk_mul_f32 v[106:107], v[106:107], v[130:131]
	v_pk_fma_f32 v[104:105], v[108:109], v[132:133], v[104:105]
	v_pk_mul_f32 v[100:101], v[100:101], v[114:115] op_sel_hi:[1,0]
	v_pk_mul_f32 v[96:97], v[96:97], v[114:115] op_sel_hi:[1,0]
	v_pk_fma_f32 v[118:119], v[110:111], v[130:131], v[118:119] neg_lo:[0,0,1] neg_hi:[0,0,1]
	v_pk_fma_f32 v[116:117], v[108:109], v[128:129], v[116:117] neg_lo:[0,0,1] neg_hi:[0,0,1]
	v_pk_fma_f32 v[106:107], v[110:111], v[134:135], v[106:107]
	v_cvt_pk_bf16_f32 v108, v116, v117
	v_cvt_pk_bf16_f32 v109, v118, v119
	v_cvt_pk_bf16_f32 v104, v104, v105
	v_pk_mul_f32 v[102:103], v[102:103], v[114:115] op_sel_hi:[1,0]
	v_cvt_pk_bf16_f32 v105, v106, v107
	ds_write2_b64 v174, v[108:109], v[104:105] offset1:4
	v_cvt_pk_bf16_f32 v100, v100, v101
	v_cvt_pk_bf16_f32 v101, v102, v103
	v_cvt_pk_bf16_f32 v96, v96, v97
	v_pk_mul_f32 v[98:99], v[98:99], v[114:115] op_sel_hi:[1,0]
	s_and_b64 vcc, exec, s[10:11]
	v_cvt_pk_bf16_f32 v97, v98, v99
	ds_write2_b64 v174, v[100:101], v[96:97] offset0:8 offset1:12
	v_or_b32_e32 v96, s26, v168
	v_lshlrev_b32_e32 v96, s53, v96
	v_bitop3_b32 v97, s26, v178, v168 bitop3:0xc8
	v_and_b32_e32 v96, 0x3fff, v96
	ds_read_b128 v[100:103], v175
	ds_read_b32 v98, v184 offset:128
	v_or_b32_e32 v96, s58, v96
	v_lshrrev_b32_e32 v97, s51, v97
	v_add_u32_e32 v96, v96, v97
	v_ashrrev_i32_e32 v97, 31, v96
	v_lshlrev_b64 v[96:97], 8, v[96:97]
	v_lshl_add_u64 v[96:97], v[112:113], 0, v[96:97]
	s_waitcnt lgkmcnt(1)
	global_store_dwordx4 v[96:97], v[100:103], off nt
	v_or_b32_e32 v96, s26, v169
	v_lshlrev_b32_e32 v96, s53, v96
	v_bitop3_b32 v97, s26, v179, v169 bitop3:0xc8
	v_and_b32_e32 v96, 0x3fff, v96
	ds_read_b128 v[100:103], v175 offset:1152
	v_or_b32_e32 v96, s58, v96
	v_lshrrev_b32_e32 v97, s51, v97
	v_add_u32_e32 v96, v96, v97
	v_ashrrev_i32_e32 v97, 31, v96
	v_lshlrev_b64 v[96:97], 8, v[96:97]
	v_lshl_add_u64 v[96:97], v[112:113], 0, v[96:97]
	s_waitcnt lgkmcnt(0)
	global_store_dwordx4 v[96:97], v[100:103], off nt
	s_or_b32 s26, s62, 32
	v_mov_b32_e32 v96, 1.0
	v_mov_b32_e32 v100, 0
	v_mov_b32_e32 v102, 0
	v_mov_b32_e32 v103, 0
	v_mov_b32_e32 v104, 0
	v_mov_b32_e32 v105, 0
	v_mov_b32_e32 v106, 1.0
	v_mov_b32_e32 v107, 1.0
	v_mov_b32_e32 v108, 1.0
	v_mov_b32_e32 v109, 1.0
	s_cbranch_vccnz .LBB0_608
	v_mov_b64_e32 v[106:107], v[198:199]
	v_mov_b64_e32 v[108:109], v[200:201]
	v_mov_b64_e32 v[102:103], v[202:203]
	v_mov_b64_e32 v[104:105], v[204:205]
.LBB0_608:
	v_pk_mul_f32 v[88:89], v[88:89], v[98:99] op_sel_hi:[1,0]
	v_pk_mul_f32 v[92:93], v[92:93], v[98:99] op_sel_hi:[1,0]
	v_pk_mul_f32 v[90:91], v[90:91], v[98:99] op_sel_hi:[1,0]
	v_pk_mul_f32 v[110:111], v[88:89], v[102:103]
	v_pk_mul_f32 v[88:89], v[88:89], v[106:107]
	v_pk_mul_f32 v[94:95], v[94:95], v[98:99] op_sel_hi:[1,0]
	v_pk_mul_f32 v[114:115], v[90:91], v[104:105]
	v_pk_mul_f32 v[90:91], v[90:91], v[108:109]
	v_pk_fma_f32 v[88:89], v[92:93], v[102:103], v[88:89]
	v_pk_mul_f32 v[84:85], v[84:85], v[98:99] op_sel_hi:[1,0]
	v_pk_mul_f32 v[80:81], v[80:81], v[98:99] op_sel_hi:[1,0]
	v_pk_fma_f32 v[114:115], v[94:95], v[108:109], v[114:115] neg_lo:[0,0,1] neg_hi:[0,0,1]
	v_pk_fma_f32 v[110:111], v[92:93], v[106:107], v[110:111] neg_lo:[0,0,1] neg_hi:[0,0,1]
	v_pk_fma_f32 v[90:91], v[94:95], v[104:105], v[90:91]
	v_cvt_pk_bf16_f32 v92, v110, v111
	v_cvt_pk_bf16_f32 v93, v114, v115
	v_cvt_pk_bf16_f32 v88, v88, v89
	v_pk_mul_f32 v[86:87], v[86:87], v[98:99] op_sel_hi:[1,0]
	v_cvt_pk_bf16_f32 v89, v90, v91
	ds_write2_b64 v174, v[92:93], v[88:89] offset1:4
	v_cvt_pk_bf16_f32 v84, v84, v85
	v_cvt_pk_bf16_f32 v85, v86, v87
	v_cvt_pk_bf16_f32 v80, v80, v81
	v_pk_mul_f32 v[82:83], v[82:83], v[98:99] op_sel_hi:[1,0]
	s_and_b64 vcc, exec, s[10:11]
	v_cvt_pk_bf16_f32 v81, v82, v83
	ds_write2_b64 v174, v[84:85], v[80:81] offset0:8 offset1:12
	v_or_b32_e32 v80, s26, v168
	v_lshlrev_b32_e32 v80, s53, v80
	v_bitop3_b32 v81, s26, v180, v168 bitop3:0xc8
	v_and_b32_e32 v80, 0x3fff, v80
	v_or_b32_e32 v80, s58, v80
	v_lshrrev_b32_e32 v81, s51, v81
	ds_read_b128 v[82:85], v175
	v_add_u32_e32 v80, v80, v81
	v_ashrrev_i32_e32 v81, 31, v80
	v_lshlrev_b64 v[80:81], 8, v[80:81]
	v_lshl_add_u64 v[86:87], v[112:113], 0, v[80:81]
	v_or_b32_e32 v81, s26, v169
	v_lshlrev_b32_e32 v81, s53, v81
	ds_read_b32 v80, v184 offset:192
	s_waitcnt lgkmcnt(1)
	global_store_dwordx4 v[86:87], v[82:85], off nt
	v_bitop3_b32 v86, s26, v181, v169 bitop3:0xc8
	v_and_b32_e32 v81, 0x3fff, v81
	ds_read_b128 v[82:85], v175 offset:1152
	v_or_b32_e32 v81, s58, v81
	v_lshrrev_b32_e32 v86, s51, v86
	v_add_u32_e32 v86, v81, v86
	v_ashrrev_i32_e32 v87, 31, v86
	v_lshlrev_b64 v[86:87], 8, v[86:87]
	v_lshl_add_u64 v[86:87], v[112:113], 0, v[86:87]
	s_or_b32 s26, s62, 48
	v_mov_b32_e32 v101, 0
	v_mov_b32_e32 v102, 0
	v_mov_b32_e32 v103, 0
	v_mov_b32_e32 v97, 1.0
	v_mov_b32_e32 v98, 1.0
	v_mov_b32_e32 v99, 1.0
	s_waitcnt lgkmcnt(0)
	global_store_dwordx4 v[86:87], v[82:85], off nt
	s_cbranch_vccnz .LBB0_610
	v_mov_b64_e32 v[96:97], v[206:207]
	v_mov_b64_e32 v[98:99], v[208:209]
	v_mov_b64_e32 v[100:101], v[212:213]
	v_mov_b64_e32 v[102:103], v[214:215]
; #define PG8_LAS __attribute__((address_space(3)))
; __device__ __forceinline__ unsigned cvt_pk_bf16(float lo, float hi) { unsigned r; asm volatile("v_cvt_pk_bf16_f32 %0, %1, %2" : "=v"(r) : "v"(lo), "v"(hi)); return r; }
; template <int LAYOUT> __device__ __forceinline__ void staged_store_bf16(PG8_LAS unsigned char* stg, bf16_t* O, size_t ldc, int rowg0, int pn, int wc, int lane) {
;     const int p = lane & 7;
; #pragma unroll
;     for (int hr = 0; hr < 2; ++hr) { const int r = 8 * hr + (lane >> 3), rowg = rowg0 + r; const u32x4 w = *(const PG8_LAS u32x4*)(stg + r * STG_ROW + p * 16);
;         if (LAYOUT == 0) __builtin_nontemporal_store(w, (u32x4*)(O + (size_t)rowg * ldc + pn * BM + wc * 64 + p * 8));
;         else { const int P = 2 * pn + (wc >> 1); int drow = rowg;
;             if (LAYOUT == 2) { const int sh = 2 * (P / 24), t = rowg & 16383; drow = (rowg & ~16383) + ((t & ((1 << sh) - 1)) << (14 - sh)) + (t >> sh); }
;             __builtin_nontemporal_store(w, (u32x4*)(O + (size_t)P * PLANE + (size_t)drow * 128 + (wc & 1) * 64 + p * 8)); } }
;     __device__ __forceinline__ void operator()(const f32x4 (&acc)[2][2][4][2], const Unit& u, int wr, int wc, int fr, int fq) const {
;     ...
;                 const int rowg0 = u.pm * BM + ai * HALF + wr * 64 + m * 16, row = rowg0 + fr; const float rs = rtab[ai * HALF + wr * 64 + m * 16 + fr];
;                 f32x4 c4 = {1.f, 1.f, 1.f, 1.f}, s4 = {0.f, 0.f, 0.f, 0.f};
;                 if (rot) { const int t = row & 16383; c4 = *(const f32x4*)(cst + t * 16 + 4 * fq); s4 = *(const f32x4*)(snt + t * 16 + 4 * fq); }
; #pragma unroll
;                 for (int bj = 0; bj < 2; ++bj) {
;                     const f32x4 a = acc[ai][bj][m][0] * rs, b = acc[ai][bj][m][1] * rs;
;                     const f32x4 a2 = (bj == 0) ? a * c4 - b * s4 : a, b2 = (bj == 0) ? b * c4 + a * s4 : b;
;                     u32x2 w0, w1; w0.x = cvt_pk_bf16(a2[0], a2[1]); w0.y = cvt_pk_bf16(a2[2], a2[3]); w1.x = cvt_pk_bf16(b2[0], b2[1]); w1.y = cvt_pk_bf16(b2[2], b2[3]);
;                     *(PG8_LAS u32x2*)(stg + fr * STG_ROW + bj * 64 + fq * 8) = w0; *(PG8_LAS u32x2*)(stg + fr * STG_ROW + bj * 64 + 32 + fq * 8) = w1; }
;                 staged_store_bf16<2>(stg, O, (size_t)ldc, rowg0, u.pn, wc, lane);
.LBB0_610:
	v_pk_mul_f32 v[72:73], v[72:73], v[80:81] op_sel_hi:[1,0]
	v_pk_mul_f32 v[76:77], v[76:77], v[80:81] op_sel_hi:[1,0]
	v_pk_mul_f32 v[74:75], v[74:75], v[80:81] op_sel_hi:[1,0]
	v_pk_mul_f32 v[82:83], v[72:73], v[100:101]
	v_pk_mul_f32 v[72:73], v[72:73], v[96:97]
	v_pk_mul_f32 v[78:79], v[78:79], v[80:81] op_sel_hi:[1,0]
	v_pk_mul_f32 v[84:85], v[74:75], v[102:103]
	v_pk_mul_f32 v[74:75], v[74:75], v[98:99]
	v_pk_fma_f32 v[72:73], v[76:77], v[100:101], v[72:73]
	v_pk_mul_f32 v[68:69], v[68:69], v[80:81] op_sel_hi:[1,0]
	v_pk_mul_f32 v[64:65], v[64:65], v[80:81] op_sel_hi:[1,0]
	v_pk_fma_f32 v[84:85], v[78:79], v[98:99], v[84:85] neg_lo:[0,0,1] neg_hi:[0,0,1]
	v_pk_fma_f32 v[82:83], v[76:77], v[96:97], v[82:83] neg_lo:[0,0,1] neg_hi:[0,0,1]
	v_pk_fma_f32 v[74:75], v[78:79], v[102:103], v[74:75]
	v_cvt_pk_bf16_f32 v76, v82, v83
	v_cvt_pk_bf16_f32 v77, v84, v85
	v_cvt_pk_bf16_f32 v72, v72, v73
	v_pk_mul_f32 v[70:71], v[70:71], v[80:81] op_sel_hi:[1,0]
	v_cvt_pk_bf16_f32 v73, v74, v75
	ds_write2_b64 v174, v[76:77], v[72:73] offset1:4
	v_cvt_pk_bf16_f32 v68, v68, v69
	v_cvt_pk_bf16_f32 v69, v70, v71
	v_cvt_pk_bf16_f32 v64, v64, v65
	v_pk_mul_f32 v[66:67], v[66:67], v[80:81] op_sel_hi:[1,0]
	s_and_b64 vcc, exec, s[10:11]
	v_cvt_pk_bf16_f32 v65, v66, v67
	ds_write2_b64 v174, v[68:69], v[64:65] offset0:8 offset1:12
	v_or_b32_e32 v64, s26, v168
	v_lshlrev_b32_e32 v64, s53, v64
	v_bitop3_b32 v65, s26, v182, v168 bitop3:0xc8
	v_and_b32_e32 v64, 0x3fff, v64
	ds_read_b128 v[68:71], v175
	ds_read_b32 v66, v184 offset:512
	v_or_b32_e32 v64, s58, v64
	v_lshrrev_b32_e32 v65, s51, v65
	v_add_u32_e32 v64, v64, v65
	v_ashrrev_i32_e32 v65, 31, v64
	v_lshlrev_b64 v[64:65], 8, v[64:65]
	v_lshl_add_u64 v[64:65], v[112:113], 0, v[64:65]
	s_waitcnt lgkmcnt(1)
	global_store_dwordx4 v[64:65], v[68:71], off nt
	v_or_b32_e32 v64, s26, v169
	v_lshlrev_b32_e32 v64, s53, v64
	v_bitop3_b32 v65, s26, v183, v169 bitop3:0xc8
	v_and_b32_e32 v64, 0x3fff, v64
	ds_read_b128 v[68:71], v175 offset:1152
	v_or_b32_e32 v64, s58, v64
	v_lshrrev_b32_e32 v65, s51, v65
	v_add_u32_e32 v64, v64, v65
	v_ashrrev_i32_e32 v65, 31, v64
	v_lshlrev_b64 v[64:65], 8, v[64:65]
	v_lshl_add_u64 v[64:65], v[112:113], 0, v[64:65]
	s_waitcnt lgkmcnt(0)
	global_store_dwordx4 v[64:65], v[68:71], off nt
	s_add_i32 s58, s62, 0x80
	v_mov_b32_e32 v64, 1.0
	v_mov_b32_e32 v68, 0
	v_mov_b32_e32 v70, 0
	v_mov_b32_e32 v71, 0
	v_mov_b32_e32 v72, 0
	v_mov_b32_e32 v73, 0
	v_mov_b32_e32 v74, 1.0
	v_mov_b32_e32 v75, 1.0
	v_mov_b32_e32 v76, 1.0
	v_mov_b32_e32 v77, 1.0
	s_cbranch_vccnz .LBB0_612
	v_mov_b64_e32 v[74:75], v[216:217]
	v_mov_b64_e32 v[76:77], v[218:219]
	v_mov_b64_e32 v[70:71], v[220:221]
	v_mov_b64_e32 v[72:73], v[222:223]
.LBB0_612:
	v_pk_mul_f32 v[56:57], v[56:57], v[66:67] op_sel_hi:[1,0]
	v_pk_mul_f32 v[60:61], v[60:61], v[66:67] op_sel_hi:[1,0]
	v_pk_mul_f32 v[58:59], v[58:59], v[66:67] op_sel_hi:[1,0]
	v_pk_mul_f32 v[78:79], v[56:57], v[70:71]
	v_pk_mul_f32 v[56:57], v[56:57], v[74:75]
	v_pk_mul_f32 v[62:63], v[62:63], v[66:67] op_sel_hi:[1,0]
	v_pk_mul_f32 v[80:81], v[58:59], v[72:73]
	v_pk_mul_f32 v[58:59], v[58:59], v[76:77]
	v_pk_fma_f32 v[56:57], v[60:61], v[70:71], v[56:57]
	v_pk_mul_f32 v[52:53], v[52:53], v[66:67] op_sel_hi:[1,0]
	v_pk_mul_f32 v[48:49], v[48:49], v[66:67] op_sel_hi:[1,0]
	v_pk_fma_f32 v[80:81], v[62:63], v[76:77], v[80:81] neg_lo:[0,0,1] neg_hi:[0,0,1]
	v_pk_fma_f32 v[78:79], v[60:61], v[74:75], v[78:79] neg_lo:[0,0,1] neg_hi:[0,0,1]
	v_pk_fma_f32 v[58:59], v[62:63], v[72:73], v[58:59]
	v_cvt_pk_bf16_f32 v60, v78, v79
	v_cvt_pk_bf16_f32 v61, v80, v81
	v_cvt_pk_bf16_f32 v56, v56, v57
	v_pk_mul_f32 v[54:55], v[54:55], v[66:67] op_sel_hi:[1,0]
	v_cvt_pk_bf16_f32 v57, v58, v59
	ds_write2_b64 v174, v[60:61], v[56:57] offset1:4
	v_cvt_pk_bf16_f32 v52, v52, v53
	v_cvt_pk_bf16_f32 v53, v54, v55
	v_cvt_pk_bf16_f32 v48, v48, v49
	v_pk_mul_f32 v[50:51], v[50:51], v[66:67] op_sel_hi:[1,0]
	v_mov_b32_e32 v56, s58
	v_cvt_pk_bf16_f32 v49, v50, v51
	ds_write2_b64 v174, v[52:53], v[48:49] offset0:8 offset1:12
	v_or_b32_e32 v48, s58, v168
	v_bitop3_b32 v49, s58, v176, v168 bitop3:0xc8
	v_lshlrev_b32_e32 v48, s53, v48
	ds_read_b128 v[50:53], v175
	v_bfi_b32 v48, s84, v48, v56
	v_lshrrev_b32_e32 v49, s51, v49
	v_add_u32_e32 v48, v48, v49
	v_ashrrev_i32_e32 v49, 31, v48
	v_lshlrev_b64 v[48:49], 8, v[48:49]
	v_lshl_add_u64 v[54:55], v[112:113], 0, v[48:49]
	v_or_b32_e32 v49, s58, v169
	ds_read_b32 v48, v184 offset:576
	s_waitcnt lgkmcnt(1)
	global_store_dwordx4 v[54:55], v[50:53], off nt
	v_bitop3_b32 v54, s58, v177, v169 bitop3:0xc8
	v_lshlrev_b32_e32 v49, s53, v49
	ds_read_b128 v[50:53], v175 offset:1152
	v_bfi_b32 v49, s84, v49, v56
	v_lshrrev_b32_e32 v54, s51, v54
	v_add_u32_e32 v54, v49, v54
	v_ashrrev_i32_e32 v55, 31, v54
	v_lshlrev_b64 v[54:55], 8, v[54:55]
	v_lshl_add_u64 v[54:55], v[112:113], 0, v[54:55]
	s_or_b32 s26, s58, 16
	s_and_b64 vcc, exec, s[10:11]
	v_mov_b32_e32 v69, 0
	v_mov_b32_e32 v70, 0
	v_mov_b32_e32 v71, 0
	v_mov_b32_e32 v65, 1.0
	v_mov_b32_e32 v66, 1.0
	v_mov_b32_e32 v67, 1.0
	s_waitcnt lgkmcnt(0)
	global_store_dwordx4 v[54:55], v[50:53], off nt
	s_cbranch_vccnz .LBB0_614
	v_mov_b64_e32 v[64:65], v[224:225]
	v_mov_b64_e32 v[66:67], v[226:227]
	v_mov_b64_e32 v[68:69], v[228:229]
	v_mov_b64_e32 v[70:71], v[230:231]
; #define PG8_LAS __attribute__((address_space(3)))
; __device__ __forceinline__ unsigned cvt_pk_bf16(float lo, float hi) { unsigned r; asm volatile("v_cvt_pk_bf16_f32 %0, %1, %2" : "=v"(r) : "v"(lo), "v"(hi)); return r; }
; template <int LAYOUT> __device__ __forceinline__ void staged_store_bf16(PG8_LAS unsigned char* stg, bf16_t* O, size_t ldc, int rowg0, int pn, int wc, int lane) {
;     const int p = lane & 7;
; #pragma unroll
;     for (int hr = 0; hr < 2; ++hr) { const int r = 8 * hr + (lane >> 3), rowg = rowg0 + r; const u32x4 w = *(const PG8_LAS u32x4*)(stg + r * STG_ROW + p * 16);
;         if (LAYOUT == 0) __builtin_nontemporal_store(w, (u32x4*)(O + (size_t)rowg * ldc + pn * BM + wc * 64 + p * 8));
;         else { const int P = 2 * pn + (wc >> 1); int drow = rowg;
;             if (LAYOUT == 2) { const int sh = 2 * (P / 24), t = rowg & 16383; drow = (rowg & ~16383) + ((t & ((1 << sh) - 1)) << (14 - sh)) + (t >> sh); }
;             __builtin_nontemporal_store(w, (u32x4*)(O + (size_t)P * PLANE + (size_t)drow * 128 + (wc & 1) * 64 + p * 8)); } }
;     __device__ __forceinline__ void operator()(const f32x4 (&acc)[2][2][4][2], const Unit& u, int wr, int wc, int fr, int fq) const {
;     ...
;                 const int rowg0 = u.pm * BM + ai * HALF + wr * 64 + m * 16, row = rowg0 + fr; const float rs = rtab[ai * HALF + wr * 64 + m * 16 + fr];
;                 f32x4 c4 = {1.f, 1.f, 1.f, 1.f}, s4 = {0.f, 0.f, 0.f, 0.f};
;                 if (rot) { const int t = row & 16383; c4 = *(const f32x4*)(cst + t * 16 + 4 * fq); s4 = *(const f32x4*)(snt + t * 16 + 4 * fq); }
; #pragma unroll
;                 for (int bj = 0; bj < 2; ++bj) {
;                     const f32x4 a = acc[ai][bj][m][0] * rs, b = acc[ai][bj][m][1] * rs;
;                     const f32x4 a2 = (bj == 0) ? a * c4 - b * s4 : a, b2 = (bj == 0) ? b * c4 + a * s4 : b;
;                     u32x2 w0, w1; w0.x = cvt_pk_bf16(a2[0], a2[1]); w0.y = cvt_pk_bf16(a2[2], a2[3]); w1.x = cvt_pk_bf16(b2[0], b2[1]); w1.y = cvt_pk_bf16(b2[2], b2[3]);
;                     *(PG8_LAS u32x2*)(stg + fr * STG_ROW + bj * 64 + fq * 8) = w0; *(PG8_LAS u32x2*)(stg + fr * STG_ROW + bj * 64 + 32 + fq * 8) = w1; }
;                 staged_store_bf16<2>(stg, O, (size_t)ldc, rowg0, u.pn, wc, lane);
.LBB0_614:
	v_pk_mul_f32 v[40:41], v[40:41], v[48:49] op_sel_hi:[1,0]
	v_pk_mul_f32 v[44:45], v[44:45], v[48:49] op_sel_hi:[1,0]
	v_pk_mul_f32 v[42:43], v[42:43], v[48:49] op_sel_hi:[1,0]
	v_pk_mul_f32 v[50:51], v[40:41], v[68:69]
	v_pk_mul_f32 v[40:41], v[40:41], v[64:65]
	v_pk_mul_f32 v[46:47], v[46:47], v[48:49] op_sel_hi:[1,0]
	v_pk_mul_f32 v[52:53], v[42:43], v[70:71]
	v_pk_mul_f32 v[42:43], v[42:43], v[66:67]
	v_pk_fma_f32 v[40:41], v[44:45], v[68:69], v[40:41]
	v_pk_mul_f32 v[36:37], v[36:37], v[48:49] op_sel_hi:[1,0]
	v_pk_mul_f32 v[32:33], v[32:33], v[48:49] op_sel_hi:[1,0]
	v_pk_fma_f32 v[52:53], v[46:47], v[66:67], v[52:53] neg_lo:[0,0,1] neg_hi:[0,0,1]
	v_pk_fma_f32 v[50:51], v[44:45], v[64:65], v[50:51] neg_lo:[0,0,1] neg_hi:[0,0,1]
	v_pk_fma_f32 v[42:43], v[46:47], v[70:71], v[42:43]
	v_cvt_pk_bf16_f32 v44, v50, v51
	v_cvt_pk_bf16_f32 v45, v52, v53
	v_cvt_pk_bf16_f32 v40, v40, v41
	v_pk_mul_f32 v[38:39], v[38:39], v[48:49] op_sel_hi:[1,0]
	v_cvt_pk_bf16_f32 v41, v42, v43
	ds_write2_b64 v174, v[44:45], v[40:41] offset1:4
	v_cvt_pk_bf16_f32 v36, v36, v37
	v_cvt_pk_bf16_f32 v37, v38, v39
	v_cvt_pk_bf16_f32 v32, v32, v33
	v_pk_mul_f32 v[34:35], v[34:35], v[48:49] op_sel_hi:[1,0]
	s_and_b32 s60, s58, 0xffffc000
	v_cvt_pk_bf16_f32 v33, v34, v35
	ds_write2_b64 v174, v[36:37], v[32:33] offset0:8 offset1:12
	v_or_b32_e32 v32, s26, v168
	v_lshlrev_b32_e32 v32, s53, v32
	v_bitop3_b32 v33, s26, v178, v168 bitop3:0xc8
	v_and_b32_e32 v32, 0x3fff, v32
	ds_read_b128 v[36:39], v175
	ds_read_b32 v34, v184 offset:640
	v_or_b32_e32 v32, s60, v32
	v_lshrrev_b32_e32 v33, s51, v33
	v_add_u32_e32 v32, v32, v33
	v_ashrrev_i32_e32 v33, 31, v32
	v_lshlrev_b64 v[32:33], 8, v[32:33]
	v_lshl_add_u64 v[32:33], v[112:113], 0, v[32:33]
	s_waitcnt lgkmcnt(1)
	global_store_dwordx4 v[32:33], v[36:39], off nt
	v_or_b32_e32 v32, s26, v169
	v_lshlrev_b32_e32 v32, s53, v32
	v_bitop3_b32 v33, s26, v179, v169 bitop3:0xc8
	v_and_b32_e32 v32, 0x3fff, v32
	ds_read_b128 v[36:39], v175 offset:1152
	v_or_b32_e32 v32, s60, v32
	v_lshrrev_b32_e32 v33, s51, v33
	v_add_u32_e32 v32, v32, v33
	v_ashrrev_i32_e32 v33, 31, v32
	v_lshlrev_b64 v[32:33], 8, v[32:33]
	v_lshl_add_u64 v[32:33], v[112:113], 0, v[32:33]
	s_waitcnt lgkmcnt(0)
	global_store_dwordx4 v[32:33], v[36:39], off nt
	s_or_b32 s26, s58, 32
	v_mov_b32_e32 v32, 1.0
	v_mov_b32_e32 v36, 0
	s_and_b64 vcc, exec, s[10:11]
	v_mov_b32_e32 v38, 0
	v_mov_b32_e32 v39, 0
	v_mov_b32_e32 v40, 0
	v_mov_b32_e32 v41, 0
	v_mov_b32_e32 v42, 1.0
	v_mov_b32_e32 v43, 1.0
	v_mov_b32_e32 v44, 1.0
	v_mov_b32_e32 v45, 1.0
	s_cbranch_vccnz .LBB0_616
	v_mov_b64_e32 v[42:43], v[232:233]
	v_mov_b64_e32 v[44:45], v[234:235]
	v_mov_b64_e32 v[38:39], v[236:237]
	v_mov_b64_e32 v[40:41], v[238:239]
; #define PG8_LAS __attribute__((address_space(3)))
; __device__ __forceinline__ unsigned cvt_pk_bf16(float lo, float hi) { unsigned r; asm volatile("v_cvt_pk_bf16_f32 %0, %1, %2" : "=v"(r) : "v"(lo), "v"(hi)); return r; }
; #define PG8_BAR __builtin_amdgcn_s_barrier()
; template <class Epi, class Sched, bool ALIGN_EPI = false, bool SP2 = false>
; __device__ __forceinline__ void gemm_phase(PG8_LAS unsigned char* lds, const Gemm g, const Sched& S, const Epi& E, int tid_in) {
;     ...
;         if constexpr (!Epi::AFTER_DRAIN) { E(acc, cur, wr, wc, fr, fq); S.done(cur); }
;         if (!has_next) break;
; #pragma unroll
;         for (int a = 0; a < 2; ++a)
; #pragma unroll
;             for (int b = 0; b < 2; ++b)
; #pragma unroll
;                 for (int m = 0; m < 4; ++m)
; #pragma unroll
;                     for (int n = 0; n < 2; ++n) acc[a][b][m][n] = (f32x4){0.f, 0.f, 0.f, 0.f};
;         cur = nxt; cA = nA; cB = nB; ++ui;
;         if constexpr (ALIGN_EPI) { if (wr == 1) PG8_BAR; }
;     __device__ __forceinline__ void operator()(const f32x4 (&acc)[2][2][4][2], const Unit& u, int wr, int wc, int fr, int fq) const {
;     ...
;                 const int rowg0 = u.pm * BM + ai * HALF + wr * 64 + m * 16, row = rowg0 + fr; const float rs = rtab[ai * HALF + wr * 64 + m * 16 + fr];
;                 f32x4 c4 = {1.f, 1.f, 1.f, 1.f}, s4 = {0.f, 0.f, 0.f, 0.f};
;                 if (rot) { const int t = row & 16383; c4 = *(const f32x4*)(cst + t * 16 + 4 * fq); s4 = *(const f32x4*)(snt + t * 16 + 4 * fq); }
; #pragma unroll
;                 for (int bj = 0; bj < 2; ++bj) {
;                     const f32x4 a = acc[ai][bj][m][0] * rs, b = acc[ai][bj][m][1] * rs;
;                     const f32x4 a2 = (bj == 0) ? a * c4 - b * s4 : a, b2 = (bj == 0) ? b * c4 + a * s4 : b;
;                     u32x2 w0, w1; w0.x = cvt_pk_bf16(a2[0], a2[1]); w0.y = cvt_pk_bf16(a2[2], a2[3]); w1.x = cvt_pk_bf16(b2[0], b2[1]); w1.y = cvt_pk_bf16(b2[2], b2[3]);
;                     *(PG8_LAS u32x2*)(stg + fr * STG_ROW + bj * 64 + fq * 8) = w0; *(PG8_LAS u32x2*)(stg + fr * STG_ROW + bj * 64 + 32 + fq * 8) = w1; }
;                 staged_store_bf16<2>(stg, O, (size_t)ldc, rowg0, u.pn, wc, lane);
.LBB0_616:
	v_pk_mul_f32 v[24:25], v[24:25], v[34:35] op_sel_hi:[1,0]
	v_pk_mul_f32 v[28:29], v[28:29], v[34:35] op_sel_hi:[1,0]
	v_pk_mul_f32 v[26:27], v[26:27], v[34:35] op_sel_hi:[1,0]
	v_pk_mul_f32 v[46:47], v[24:25], v[38:39]
	v_pk_mul_f32 v[24:25], v[24:25], v[42:43]
	v_pk_mul_f32 v[30:31], v[30:31], v[34:35] op_sel_hi:[1,0]
	v_pk_mul_f32 v[48:49], v[26:27], v[40:41]
	v_pk_mul_f32 v[26:27], v[26:27], v[44:45]
	v_pk_fma_f32 v[24:25], v[28:29], v[38:39], v[24:25]
	v_pk_mul_f32 v[20:21], v[20:21], v[34:35] op_sel_hi:[1,0]
	v_pk_mul_f32 v[16:17], v[16:17], v[34:35] op_sel_hi:[1,0]
	v_pk_fma_f32 v[48:49], v[30:31], v[44:45], v[48:49] neg_lo:[0,0,1] neg_hi:[0,0,1]
	v_pk_fma_f32 v[46:47], v[28:29], v[42:43], v[46:47] neg_lo:[0,0,1] neg_hi:[0,0,1]
	v_pk_fma_f32 v[26:27], v[30:31], v[40:41], v[26:27]
	v_cvt_pk_bf16_f32 v28, v46, v47
	v_cvt_pk_bf16_f32 v29, v48, v49
	v_cvt_pk_bf16_f32 v24, v24, v25
	v_pk_mul_f32 v[22:23], v[22:23], v[34:35] op_sel_hi:[1,0]
	v_cvt_pk_bf16_f32 v25, v26, v27
	ds_write2_b64 v174, v[28:29], v[24:25] offset1:4
	v_cvt_pk_bf16_f32 v20, v20, v21
	v_cvt_pk_bf16_f32 v21, v22, v23
	v_cvt_pk_bf16_f32 v16, v16, v17
	v_pk_mul_f32 v[18:19], v[18:19], v[34:35] op_sel_hi:[1,0]
	s_and_b64 vcc, exec, s[10:11]
	v_cvt_pk_bf16_f32 v17, v18, v19
	ds_write2_b64 v174, v[20:21], v[16:17] offset0:8 offset1:12
	v_or_b32_e32 v16, s26, v168
	v_lshlrev_b32_e32 v16, s53, v16
	v_bitop3_b32 v17, s26, v180, v168 bitop3:0xc8
	v_and_b32_e32 v16, 0x3fff, v16
	v_or_b32_e32 v16, s60, v16
	v_lshrrev_b32_e32 v17, s51, v17
	ds_read_b128 v[18:21], v175
	v_add_u32_e32 v16, v16, v17
	v_ashrrev_i32_e32 v17, 31, v16
	v_lshlrev_b64 v[16:17], 8, v[16:17]
	v_lshl_add_u64 v[22:23], v[112:113], 0, v[16:17]
	v_or_b32_e32 v17, s26, v169
	v_lshlrev_b32_e32 v17, s53, v17
	ds_read_b32 v16, v184 offset:704
	s_waitcnt lgkmcnt(1)
	global_store_dwordx4 v[22:23], v[18:21], off nt
	v_bitop3_b32 v22, s26, v181, v169 bitop3:0xc8
	v_and_b32_e32 v17, 0x3fff, v17
	ds_read_b128 v[18:21], v175 offset:1152
	v_or_b32_e32 v17, s60, v17
	v_lshrrev_b32_e32 v22, s51, v22
	v_add_u32_e32 v22, v17, v22
	v_ashrrev_i32_e32 v23, 31, v22
	v_lshlrev_b64 v[22:23], 8, v[22:23]
	v_lshl_add_u64 v[22:23], v[112:113], 0, v[22:23]
	s_or_b32 s26, s58, 48
	v_mov_b32_e32 v37, 0
	v_mov_b32_e32 v38, 0
	v_mov_b32_e32 v39, 0
	v_mov_b32_e32 v33, 1.0
	v_mov_b32_e32 v34, 1.0
	v_mov_b32_e32 v35, 1.0
	s_waitcnt lgkmcnt(0)
	global_store_dwordx4 v[22:23], v[18:21], off nt
	s_cbranch_vccnz .LBB0_618
	v_mov_b64_e32 v[32:33], v[240:241]
	v_mov_b64_e32 v[34:35], v[242:243]
	v_mov_b64_e32 v[36:37], v[244:245]
	v_mov_b64_e32 v[38:39], v[246:247]
.LBB0_618:
	v_pk_mul_f32 v[8:9], v[8:9], v[16:17] op_sel_hi:[1,0]
	v_pk_mul_f32 v[12:13], v[12:13], v[16:17] op_sel_hi:[1,0]
	v_pk_mul_f32 v[10:11], v[10:11], v[16:17] op_sel_hi:[1,0]
	v_pk_mul_f32 v[18:19], v[8:9], v[36:37]
	v_pk_mul_f32 v[8:9], v[8:9], v[32:33]
	v_pk_mul_f32 v[14:15], v[14:15], v[16:17] op_sel_hi:[1,0]
	v_pk_mul_f32 v[20:21], v[10:11], v[38:39]
	v_pk_mul_f32 v[10:11], v[10:11], v[34:35]
	v_pk_fma_f32 v[8:9], v[12:13], v[36:37], v[8:9]
	v_pk_mul_f32 v[4:5], v[4:5], v[16:17] op_sel_hi:[1,0]
	v_pk_fma_f32 v[20:21], v[14:15], v[34:35], v[20:21] neg_lo:[0,0,1] neg_hi:[0,0,1]
	v_pk_fma_f32 v[18:19], v[12:13], v[32:33], v[18:19] neg_lo:[0,0,1] neg_hi:[0,0,1]
	v_pk_fma_f32 v[10:11], v[14:15], v[38:39], v[10:11]
	v_cvt_pk_bf16_f32 v12, v18, v19
	v_cvt_pk_bf16_f32 v13, v20, v21
	v_cvt_pk_bf16_f32 v8, v8, v9
	v_pk_mul_f32 v[0:1], v[0:1], v[16:17] op_sel_hi:[1,0]
	v_cvt_pk_bf16_f32 v9, v10, v11
	ds_write2_b64 v174, v[12:13], v[8:9] offset1:4
	v_cvt_pk_bf16_f32 v4, v4, v5
	v_pk_mul_f32 v[6:7], v[6:7], v[16:17] op_sel_hi:[1,0]
	v_pk_mul_f32 v[2:3], v[2:3], v[16:17] op_sel_hi:[1,0]
	v_cvt_pk_bf16_f32 v5, v6, v7
	v_cvt_pk_bf16_f32 v0, v0, v1
	s_andn2_b64 vcc, exec, s[8:9]
	v_cvt_pk_bf16_f32 v1, v2, v3
	ds_write2_b64 v174, v[4:5], v[0:1] offset0:8 offset1:12
	v_or_b32_e32 v4, s26, v168
	v_lshlrev_b32_e32 v4, s53, v4
	v_bitop3_b32 v5, s26, v182, v168 bitop3:0xc8
	v_and_b32_e32 v4, 0x3fff, v4
	ds_read_b128 v[0:3], v175
	v_or_b32_e32 v4, s60, v4
	v_lshrrev_b32_e32 v5, s51, v5
	v_add_u32_e32 v4, v4, v5
	v_ashrrev_i32_e32 v5, 31, v4
	v_lshlrev_b64 v[4:5], 8, v[4:5]
	v_lshl_add_u64 v[8:9], v[112:113], 0, v[4:5]
	ds_read_b128 v[4:7], v175 offset:1152
	s_waitcnt lgkmcnt(1)
	global_store_dwordx4 v[8:9], v[0:3], off nt
	s_mov_b64 s[8:9], -1
	s_nop 0
	v_or_b32_e32 v0, s26, v169
	v_lshlrev_b32_e32 v0, s53, v0
	v_bitop3_b32 v1, s26, v183, v169 bitop3:0xc8
	v_and_b32_e32 v0, 0x3fff, v0
	v_or_b32_e32 v0, s60, v0
	v_lshrrev_b32_e32 v1, s51, v1
	v_add_u32_e32 v0, v0, v1
	v_ashrrev_i32_e32 v1, 31, v0
	v_lshlrev_b64 v[0:1], 8, v[0:1]
	v_lshl_add_u64 v[0:1], v[112:113], 0, v[0:1]
	s_waitcnt lgkmcnt(0)
	global_store_dwordx4 v[0:1], v[4:7], off nt
	s_cbranch_vccnz .LBB0_593
	s_andn2_b64 vcc, exec, s[12:13]
	s_cbranch_vccnz .LBB0_592
	s_mov_b32 s98, 1
	s_branch .LBB0_592
